# attention: the static priority raise given to waves 0-3 instead of waves 4-7
# baseline (speedup 1.0000x reference)
; #define LAS __attribute__((address_space(3)))
; #define tid (otid())
; #define wave (__builtin_amdgcn_readfirstlane((int)(threadIdx.x >> 6)))
; __device__ __forceinline__ void attn_phase(LAS unsigned char* lds, const bf16_t* __restrict__ Q, const bf16_t* __restrict__ KN, const bf16_t* __restrict__ KR,
;                                            const bf16_t* __restrict__ VT, bf16_t* AO, int vcu, int G, int tid, int lane, int wave) {
;     constexpr int KP = 104, VP = 136, KBUF = 128 * KP * 2, VBUF = 64 * VP * 2, BUF = KBUF + VBUF;
;     if (wave >= 4) __builtin_amdgcn_s_setprio(1);
;     const int r32 = lane & 31, hi = lane >> 5;
;     const int pr = (r32 & ~12) | ((r32 & 4) << 1) | ((r32 & 8) >> 1);
;     const int key_l = tid >> 3, kc = tid & 7, key_r = tid >> 2, rc = tid & 3, vd = tid >> 3, vc = tid & 7;
;     for (int p = vcu; p < 512; p += G) {
; __global__ void __launch_bounds__(512, 2) mega_fwd(Args a) {
;     ...
;     attn_phase(lds, Q, KN, KR, VT, AO, vcu, G, tid, lane, wave);
.LBB0_526:
	s_or_b64 exec, exec, s[6:7]
	s_mov_b64 s[6:7], s[0:1]
	s_waitcnt lgkmcnt(0)
	s_barrier
	s_load_dwordx2 s[6:7], s[6:7], 0xb8
	v_readfirstlane_b32 s8, v195
	v_mov_b32_e32 v1, v195
	v_mov_b32_e32 v2, v195
	s_cmpk_gt_u32 s8, 0xff
	s_cbranch_scc1 .LBB0_528
	s_setprio 1
